# big-GEMM tile order panel groups 3,3,3,3,3,2 (N=1024 GEMMs 8,9)
# speedup vs baseline: 1.0031x; 1.0031x over previous
.LBB0_154:
	s_cmp_ge_u32 s3, 90
	s_cbranch_scc1 .Lto_g1_a0
	s_sub_u32 s99, s3, 0
	s_mul_hi_u32 s98, s99, 0xaaaaaaab
	s_lshr_b32 s98, s98, 1
	s_mul_i32 s100, s98, 3
	s_sub_u32 s99, s99, s100
	s_branch .Lto_j_a0
.Lto_g1_a0:
	s_cmp_ge_u32 s3, 180
	s_cbranch_scc1 .Lto_g2_a0
	s_sub_u32 s99, s3, 90
	s_mul_hi_u32 s98, s99, 0xaaaaaaab
	s_lshr_b32 s98, s98, 1
	s_mul_i32 s100, s98, 3
	s_sub_u32 s99, s99, s100
	s_add_u32 s99, s99, 3
	s_branch .Lto_j_a0
.Lto_g2_a0:
	s_cmp_ge_u32 s3, 270
	s_cbranch_scc1 .Lto_g3_a0
	s_sub_u32 s99, s3, 180
	s_mul_hi_u32 s98, s99, 0xaaaaaaab
	s_lshr_b32 s98, s98, 1
	s_mul_i32 s100, s98, 3
	s_sub_u32 s99, s99, s100
	s_add_u32 s99, s99, 6
	s_branch .Lto_j_a0
.Lto_g3_a0:
	s_cmp_ge_u32 s3, 360
	s_cbranch_scc1 .Lto_g4_a0
	s_sub_u32 s99, s3, 270
	s_mul_hi_u32 s98, s99, 0xaaaaaaab
	s_lshr_b32 s98, s98, 1
	s_mul_i32 s100, s98, 3
	s_sub_u32 s99, s99, s100
	s_add_u32 s99, s99, 9
	s_branch .Lto_j_a0
.Lto_g4_a0:
	s_cmp_ge_u32 s3, 450
	s_cbranch_scc1 .Lto_g5_a0
	s_sub_u32 s99, s3, 360
	s_mul_hi_u32 s98, s99, 0xaaaaaaab
	s_lshr_b32 s98, s98, 1
	s_mul_i32 s100, s98, 3
	s_sub_u32 s99, s99, s100
	s_add_u32 s99, s99, 12
	s_branch .Lto_j_a0
.Lto_g5_a0:
	s_sub_u32 s99, s3, 450
	s_lshr_b32 s98, s99, 1
	s_and_b32 s99, s99, 1
	s_add_u32 s99, s99, 15

.LBB0_608:
	s_cmp_ge_u32 s3, 96
	s_cbranch_scc1 .Lto_g1_a1
	s_sub_u32 s99, s3, 0
	s_mul_hi_u32 s98, s99, 0xaaaaaaab
	s_lshr_b32 s98, s98, 1
	s_mul_i32 s100, s98, 3
	s_sub_u32 s99, s99, s100
	s_branch .Lto_j_a1
.Lto_g1_a1:
	s_cmp_ge_u32 s3, 192
	s_cbranch_scc1 .Lto_g2_a1
	s_sub_u32 s99, s3, 96
	s_mul_hi_u32 s98, s99, 0xaaaaaaab
	s_lshr_b32 s98, s98, 1
	s_mul_i32 s100, s98, 3
	s_sub_u32 s99, s99, s100
	s_add_u32 s99, s99, 3
	s_branch .Lto_j_a1
.Lto_g2_a1:
	s_cmp_ge_u32 s3, 288
	s_cbranch_scc1 .Lto_g3_a1
	s_sub_u32 s99, s3, 192
	s_mul_hi_u32 s98, s99, 0xaaaaaaab
	s_lshr_b32 s98, s98, 1
	s_mul_i32 s100, s98, 3
	s_sub_u32 s99, s99, s100
	s_add_u32 s99, s99, 6
	s_branch .Lto_j_a1
.Lto_g3_a1:
	s_cmp_ge_u32 s3, 384
	s_cbranch_scc1 .Lto_g4_a1
	s_sub_u32 s99, s3, 288
	s_mul_hi_u32 s98, s99, 0xaaaaaaab
	s_lshr_b32 s98, s98, 1
	s_mul_i32 s100, s98, 3
	s_sub_u32 s99, s99, s100
	s_add_u32 s99, s99, 9
	s_branch .Lto_j_a1
.Lto_g4_a1:
	s_cmp_ge_u32 s3, 480
	s_cbranch_scc1 .Lto_g5_a1
	s_sub_u32 s99, s3, 384
	s_mul_hi_u32 s98, s99, 0xaaaaaaab
	s_lshr_b32 s98, s98, 1
	s_mul_i32 s100, s98, 3
	s_sub_u32 s99, s99, s100
	s_add_u32 s99, s99, 12
	s_branch .Lto_j_a1
.Lto_g5_a1:
	s_sub_u32 s99, s3, 480
	s_lshr_b32 s98, s99, 1
	s_and_b32 s99, s99, 1
	s_add_u32 s99, s99, 15

.LBB0_882:
	s_cmp_ge_u32 s3, 132
	s_cbranch_scc1 .Lto_g1_a2
	s_sub_u32 s99, s3, 0
	s_mul_hi_u32 s98, s99, 0xaaaaaaab
	s_lshr_b32 s98, s98, 1
	s_mul_i32 s100, s98, 3
	s_sub_u32 s99, s99, s100
	s_branch .Lto_j_a2
.Lto_g1_a2:
	s_cmp_ge_u32 s3, 264
	s_cbranch_scc1 .Lto_g2_a2
	s_sub_u32 s99, s3, 132
	s_mul_hi_u32 s98, s99, 0xaaaaaaab
	s_lshr_b32 s98, s98, 1
	s_mul_i32 s100, s98, 3
	s_sub_u32 s99, s99, s100
	s_add_u32 s99, s99, 3
	s_branch .Lto_j_a2
.Lto_g2_a2:
	s_cmp_ge_u32 s3, 396
	s_cbranch_scc1 .Lto_g3_a2
	s_sub_u32 s99, s3, 264
	s_mul_hi_u32 s98, s99, 0xaaaaaaab
	s_lshr_b32 s98, s98, 1
	s_mul_i32 s100, s98, 3
	s_sub_u32 s99, s99, s100
	s_add_u32 s99, s99, 6
	s_branch .Lto_j_a2
.Lto_g3_a2:
	s_cmp_ge_u32 s3, 528
	s_cbranch_scc1 .Lto_g4_a2
	s_sub_u32 s99, s3, 396
	s_mul_hi_u32 s98, s99, 0xaaaaaaab
	s_lshr_b32 s98, s98, 1
	s_mul_i32 s100, s98, 3
	s_sub_u32 s99, s99, s100
	s_add_u32 s99, s99, 9
	s_branch .Lto_j_a2
.Lto_g4_a2:
	s_cmp_ge_u32 s3, 660
	s_cbranch_scc1 .Lto_g5_a2
	s_sub_u32 s99, s3, 528
	s_mul_hi_u32 s98, s99, 0xaaaaaaab
	s_lshr_b32 s98, s98, 1
	s_mul_i32 s100, s98, 3
	s_sub_u32 s99, s99, s100
	s_add_u32 s99, s99, 12
	s_branch .Lto_j_a2
.Lto_g5_a2:
	s_sub_u32 s99, s3, 660
	s_lshr_b32 s98, s99, 1
	s_and_b32 s99, s99, 1
	s_add_u32 s99, s99, 15
